# MLA attention: one-barrier offset of the two wave halves (lead closes its tile with the barrier, trail takes it between QK and PV)
# baseline (speedup 1.0000x reference)
.LBB0_177:
	v_mov_b32_e32 v14, v0
	v_mov_b32_e32 v15, v0
	s_waitcnt vmcnt(0) lgkmcnt(0)
	s_barrier
	v_mov_b32_e32 v1, v0
	v_mov_b32_e32 v2, v0
	v_mov_b32_e32 v3, v0
	v_mov_b32_e32 v4, v0
	v_mov_b32_e32 v5, v0
	v_mov_b32_e32 v6, v0
	v_mov_b32_e32 v7, v0
	v_mov_b32_e32 v8, v0
	v_mov_b32_e32 v9, v0
	v_mov_b32_e32 v10, v0
	v_mov_b32_e32 v11, v0
	v_mov_b32_e32 v12, v0
	v_mov_b32_e32 v13, v0
	s_lshl_b32 s49, s49, 12
	v_mov_b64_e32 v[30:31], v[14:15]
	v_mov_b64_e32 v[46:47], v[14:15]
	v_mov_b64_e32 v[62:63], v[14:15]
	v_mad_u64_u32 v[222:223], s[30:31], s50, v238, v[190:191]
	v_mad_u64_u32 v[224:225], s[30:31], s50, v240, v[192:193]
	v_mad_u64_u32 v[226:227], s[30:31], s50, v242, v[194:195]
	v_mad_u64_u32 v[228:229], s[30:31], s50, v244, v[196:197]
	s_addk_i32 s49, 0xff80
	s_add_i32 s51, s60, 0x80
	s_mov_b32 s52, 2
	s_mov_b32 s53, 1
	s_mov_b32 s56, 0
	v_mov_b32_e32 v205, 0
	v_mov_b32_e32 v207, 0
	v_mov_b32_e32 v96, 0
	v_mov_b32_e32 v97, 0
	v_mov_b32_e32 v98, 0
	v_mov_b32_e32 v99, 0
	v_mov_b32_e32 v100, 0
	v_mov_b32_e32 v101, 0
	v_mov_b32_e32 v102, 0
	v_mov_b32_e32 v103, 0
	v_mov_b32_e32 v104, 0
	v_mov_b32_e32 v105, 0
	v_mov_b32_e32 v106, 0
	v_mov_b32_e32 v107, 0
	v_mov_b32_e32 v108, 0
	v_mov_b32_e32 v109, 0
	v_mov_b32_e32 v110, 0
	v_mov_b32_e32 v111, 0
	v_mov_b64_e32 v[28:29], v[12:13]
	v_mov_b64_e32 v[26:27], v[10:11]
	v_mov_b64_e32 v[24:25], v[8:9]
	v_mov_b64_e32 v[22:23], v[6:7]
	v_mov_b64_e32 v[20:21], v[4:5]
	v_mov_b64_e32 v[18:19], v[2:3]
	v_mov_b64_e32 v[16:17], v[0:1]
	v_mov_b64_e32 v[44:45], v[12:13]
	v_mov_b64_e32 v[42:43], v[10:11]
	v_mov_b64_e32 v[40:41], v[8:9]
	v_mov_b64_e32 v[38:39], v[6:7]
	v_mov_b64_e32 v[36:37], v[4:5]
	v_mov_b64_e32 v[34:35], v[2:3]
	v_mov_b64_e32 v[32:33], v[0:1]
	v_mov_b64_e32 v[60:61], v[12:13]
	v_mov_b64_e32 v[58:59], v[10:11]
	v_mov_b64_e32 v[56:57], v[8:9]
	v_mov_b64_e32 v[54:55], v[6:7]
	v_mov_b64_e32 v[52:53], v[4:5]
	v_mov_b64_e32 v[50:51], v[2:3]
	v_mov_b64_e32 v[48:49], v[0:1]
	s_mov_b32 s55, 0
	s_waitcnt vmcnt(0)
	s_mul_i32 s30, s56, 0x6400
	v_add_u32_e32 v209, s30, v246
	s_mul_i32 s30, s56, 0x4800
	v_add_u32_e32 v219, s30, v247
	v_readfirstlane_b32 s30, v191
	s_lshr_b32 s30, s30, 8
	s_cmp_eq_u32 s30, 0
	s_cbranch_scc0 .Latt_mlaT_top
.LBB0_178:
.LBB0_191:
	ds_read_b128 v[112:115], v209 offset:0
	ds_read_b128 v[116:119], v209 offset:12800
	ds_read_b128 v[120:123], v209 offset:32
	ds_read_b128 v[124:127], v209 offset:12832
	ds_read_b128 v[250:253], v209 offset:64
	s_cmp_eq_u32 s55, 0
	s_cbranch_scc1 .Latt_mlaL_dmaend
	s_add_i32 s30, s55, 1
	s_cmp_ge_u32 s30, s20
	s_cselect_b64 s[60:61], -1, 0
	s_cbranch_scc1 .Latt_mlaL_dmaend
	s_cmp_lt_u32 s55, 3
	s_cselect_b32 s62, s51, s49
	s_sub_i32 s62, s62, 64
	s_mul_i32 s57, s53, 0x6400
	s_add_i32 s57, s57, s42
	s_mov_b32 m0, s57
	v_mad_u32_u24 v217, s62, v237, v222
	global_load_lds_dwordx4 v217, s[2:3]
	s_add_i32 m0, s57, 0x2000
	v_mad_u32_u24 v217, s62, v239, v224
	global_load_lds_dwordx4 v217, s[2:3]
	s_add_i32 m0, s57, 0x4000
	v_mad_u32_u24 v217, s62, v241, v226
	global_load_lds_dwordx4 v217, s[2:3]
	s_ashr_i32 s63, s62, 31
	s_lshl_b64 s[30:31], s[62:63], 1
	s_mul_i32 s63, s53, 0x4800
	s_add_i32 s63, s63, s42
	s_add_i32 m0, s63, 0x12c00
	s_add_u32 s30, s21, s30
	s_addc_u32 s31, s43, s31
	global_load_lds_dwordx4 v202, s[30:31]
	s_add_i32 m0, s63, 0x14c00
	s_and_b64 vcc, exec, s[18:19]
	global_load_lds_dwordx4 v200, s[30:31]
	s_cbranch_vccz .Latt_mlaL_dmax
.Latt_mlaL_dmaend:
	s_waitcnt lgkmcnt(4)
	v_mfma_f32_32x32x16_bf16 v[64:79], v[112:115], v[130:133], v[96:111]
	ds_read_b128 v[112:115], v209 offset:12864
	s_waitcnt lgkmcnt(4)
	v_mfma_f32_32x32x16_bf16 v[80:95], v[116:119], v[130:133], v[96:111]
	ds_read_b128 v[116:119], v209 offset:96
	s_waitcnt lgkmcnt(4)
	v_mfma_f32_32x32x16_bf16 v[64:79], v[120:123], v[134:137], v[64:79]
	ds_read_b128 v[120:123], v209 offset:12896
	s_waitcnt lgkmcnt(4)
	v_mfma_f32_32x32x16_bf16 v[80:95], v[124:127], v[134:137], v[80:95]
	ds_read_b128 v[124:127], v209 offset:128
	s_waitcnt lgkmcnt(4)
	v_mfma_f32_32x32x16_bf16 v[64:79], v[250:253], v[138:141], v[64:79]
	ds_read_b128 v[250:253], v209 offset:12928
	s_waitcnt lgkmcnt(4)
	v_mfma_f32_32x32x16_bf16 v[80:95], v[112:115], v[138:141], v[80:95]
	ds_read_b128 v[112:115], v209 offset:160
	s_waitcnt lgkmcnt(4)
	v_mfma_f32_32x32x16_bf16 v[64:79], v[116:119], v[142:145], v[64:79]
	ds_read_b128 v[116:119], v209 offset:12960
	s_waitcnt lgkmcnt(4)
	v_mfma_f32_32x32x16_bf16 v[80:95], v[120:123], v[142:145], v[80:95]
	ds_read_b128 v[120:123], v209 offset:192
	s_waitcnt lgkmcnt(4)
	v_mfma_f32_32x32x16_bf16 v[64:79], v[124:127], v[146:149], v[64:79]
	ds_read_b128 v[124:127], v209 offset:12992
	s_waitcnt lgkmcnt(4)
	v_mfma_f32_32x32x16_bf16 v[80:95], v[250:253], v[146:149], v[80:95]
	ds_read_b128 v[250:253], v209 offset:224
	s_waitcnt lgkmcnt(4)
	v_mfma_f32_32x32x16_bf16 v[64:79], v[112:115], v[150:153], v[64:79]
	ds_read_b128 v[112:115], v209 offset:13024
	s_waitcnt lgkmcnt(4)
	v_mfma_f32_32x32x16_bf16 v[80:95], v[116:119], v[150:153], v[80:95]
	ds_read_b128 v[116:119], v209 offset:256
	s_waitcnt lgkmcnt(4)
	v_mfma_f32_32x32x16_bf16 v[64:79], v[120:123], v[154:157], v[64:79]
	ds_read_b128 v[120:123], v209 offset:13056
	s_waitcnt lgkmcnt(4)
	v_mfma_f32_32x32x16_bf16 v[80:95], v[124:127], v[154:157], v[80:95]
	ds_read_b128 v[124:127], v209 offset:288
	s_waitcnt lgkmcnt(4)
	v_mfma_f32_32x32x16_bf16 v[64:79], v[250:253], v[158:161], v[64:79]
	ds_read_b128 v[250:253], v209 offset:13088
	s_waitcnt lgkmcnt(4)
	v_mfma_f32_32x32x16_bf16 v[80:95], v[112:115], v[158:161], v[80:95]
	ds_read_b128 v[112:115], v209 offset:320
	s_waitcnt lgkmcnt(4)
	v_mfma_f32_32x32x16_bf16 v[64:79], v[116:119], v[162:165], v[64:79]
	ds_read_b128 v[116:119], v209 offset:13120
	s_waitcnt lgkmcnt(4)
	v_mfma_f32_32x32x16_bf16 v[80:95], v[120:123], v[162:165], v[80:95]
	ds_read_b128 v[120:123], v209 offset:352
	s_waitcnt lgkmcnt(4)
	v_mfma_f32_32x32x16_bf16 v[64:79], v[124:127], v[166:169], v[64:79]
	ds_read_b128 v[124:127], v209 offset:13152
	s_waitcnt lgkmcnt(4)
	v_mfma_f32_32x32x16_bf16 v[80:95], v[250:253], v[166:169], v[80:95]
	s_waitcnt lgkmcnt(3)
	v_mfma_f32_32x32x16_bf16 v[64:79], v[112:115], v[170:173], v[64:79]
	s_waitcnt lgkmcnt(2)
	v_mfma_f32_32x32x16_bf16 v[80:95], v[116:119], v[170:173], v[80:95]
	s_waitcnt lgkmcnt(1)
	v_mfma_f32_32x32x16_bf16 v[64:79], v[120:123], v[174:177], v[64:79]
	s_waitcnt lgkmcnt(0)
	v_mfma_f32_32x32x16_bf16 v[80:95], v[124:127], v[174:177], v[80:95]
	ds_read_b128 v[112:115], v219 offset:0
	ds_read_b128 v[116:119], v219 offset:4608
	ds_read_b128 v[120:123], v219 offset:9216
	s_cmp_eq_u32 s55, 0
	s_cselect_b32 s31, 0xff7fffff, 0
	s_nop 5
	v_max3_f32 v209, v64, v65, v66
	v_max3_f32 v211, v67, v68, v69
	v_max3_f32 v209, v209, v70, v71
	v_max3_f32 v211, v211, v72, v73
	v_max3_f32 v209, v209, v74, v75
	v_max3_f32 v211, v211, v76, v77
	v_max3_f32 v209, v209, v78, v79
	v_max3_f32 v213, v80, v81, v82
	v_max3_f32 v215, v83, v84, v85
	v_max3_f32 v213, v213, v86, v87
	v_max3_f32 v215, v215, v88, v89
	v_max3_f32 v213, v213, v90, v91
	v_max3_f32 v215, v215, v92, v93
	v_max3_f32 v213, v213, v94, v95
	v_max3_f32 v209, v209, v211, v213
	v_max_f32_e32 v209, v209, v215
	v_cmp_lt_f32_e32 vcc, s58, v209
	s_cmp_eq_u32 s55, 0
	s_cbranch_scc1 .Latt_mlaL_rare
	s_cbranch_vccnz .Latt_mlaL_rare
.Latt_mlaL_norescale:
	v_exp_f32_e32 v64, v64
	v_exp_f32_e32 v65, v65
	v_exp_f32_e32 v66, v66
	v_exp_f32_e32 v67, v67
	v_exp_f32_e32 v68, v68
	v_exp_f32_e32 v69, v69
	v_exp_f32_e32 v70, v70
	v_exp_f32_e32 v71, v71
	v_cvt_pk_bf16_f32 v124, v64, v65
	v_cvt_pk_bf16_f32 v125, v66, v67
	v_cvt_pk_bf16_f32 v126, v68, v69
	v_cvt_pk_bf16_f32 v127, v70, v71
	s_waitcnt lgkmcnt(2)
	s_nop 0
	v_mfma_f32_32x32x16_bf16 v[48:63], v[112:115], v[124:127], v[48:63]
	ds_read_b128 v[112:115], v219 offset:13824
	v_exp_f32_e32 v72, v72
	v_exp_f32_e32 v73, v73
	v_exp_f32_e32 v74, v74
	v_exp_f32_e32 v75, v75
	s_waitcnt lgkmcnt(2)
	v_mfma_f32_32x32x16_bf16 v[32:47], v[116:119], v[124:127], v[32:47]
	ds_read_b128 v[116:119], v219 offset:32
	v_cvt_pk_bf16_f32 v250, v72, v73
	v_exp_f32_e32 v76, v76
	v_exp_f32_e32 v77, v77
	v_cvt_pk_bf16_f32 v251, v74, v75
	s_waitcnt lgkmcnt(2)
	v_mfma_f32_32x32x16_bf16 v[16:31], v[120:123], v[124:127], v[16:31]
	ds_read_b128 v[120:123], v219 offset:4640
	v_exp_f32_e32 v78, v78
	v_exp_f32_e32 v79, v79
	v_cvt_pk_bf16_f32 v252, v76, v77
	v_cvt_pk_bf16_f32 v253, v78, v79
	s_waitcnt lgkmcnt(2)
	v_mfma_f32_32x32x16_bf16 v[0:15], v[112:115], v[124:127], v[0:15]
	ds_read_b128 v[112:115], v219 offset:9248
	v_add_f32_e32 v209, v64, v68
	v_add_f32_e32 v211, v65, v69
	v_add_f32_e32 v213, v66, v70
	v_add_f32_e32 v215, v67, v71
	s_waitcnt lgkmcnt(2)
	v_mfma_f32_32x32x16_bf16 v[48:63], v[116:119], v[250:253], v[48:63]
	ds_read_b128 v[64:67], v219 offset:13856
	ds_read_b128 v[68:71], v219 offset:64
	v_exp_f32_e32 v80, v80
	v_exp_f32_e32 v81, v81
	v_exp_f32_e32 v82, v82
	v_exp_f32_e32 v83, v83
	v_cvt_pk_bf16_f32 v124, v80, v81
	s_waitcnt lgkmcnt(3)
	v_mfma_f32_32x32x16_bf16 v[32:47], v[120:123], v[250:253], v[32:47]
	ds_read_b128 v[116:119], v219 offset:4672
	ds_read_b128 v[120:123], v219 offset:9280
	v_exp_f32_e32 v84, v84
	v_exp_f32_e32 v85, v85
	v_cvt_pk_bf16_f32 v125, v82, v83
	v_exp_f32_e32 v86, v86
	v_exp_f32_e32 v87, v87
	s_waitcnt lgkmcnt(4)
	v_mfma_f32_32x32x16_bf16 v[16:31], v[112:115], v[250:253], v[16:31]
	ds_read_b128 v[112:115], v219 offset:13888
	v_cvt_pk_bf16_f32 v126, v84, v85
	v_cvt_pk_bf16_f32 v127, v86, v87
	v_add_f32_e32 v209, v209, v72
	v_add_f32_e32 v211, v211, v73
	v_add_f32_e32 v213, v213, v74
	s_waitcnt lgkmcnt(4)
	v_mfma_f32_32x32x16_bf16 v[0:15], v[64:67], v[250:253], v[0:15]
	ds_read_b128 v[64:67], v219 offset:96
	v_add_f32_e32 v215, v215, v75
	v_add_f32_e32 v209, v209, v76
	v_add_f32_e32 v211, v211, v77
	v_add_f32_e32 v213, v213, v78
	v_add_f32_e32 v215, v215, v79
	s_waitcnt lgkmcnt(4)
	v_mfma_f32_32x32x16_bf16 v[48:63], v[68:71], v[124:127], v[48:63]
	ds_read_b128 v[72:75], v219 offset:4704
	ds_read_b128 v[76:79], v219 offset:9312
	v_exp_f32_e32 v88, v88
	v_exp_f32_e32 v89, v89
	v_exp_f32_e32 v90, v90
	v_exp_f32_e32 v91, v91
	v_cvt_pk_bf16_f32 v250, v88, v89
	s_waitcnt lgkmcnt(5)
	v_mfma_f32_32x32x16_bf16 v[32:47], v[116:119], v[124:127], v[32:47]
	ds_read_b128 v[68:71], v219 offset:13920
	v_exp_f32_e32 v92, v92
	v_exp_f32_e32 v93, v93
	v_cvt_pk_bf16_f32 v251, v90, v91
	v_exp_f32_e32 v94, v94
	v_exp_f32_e32 v95, v95
	s_waitcnt lgkmcnt(5)
	v_mfma_f32_32x32x16_bf16 v[16:31], v[120:123], v[124:127], v[16:31]
	v_cvt_pk_bf16_f32 v252, v92, v93
	v_cvt_pk_bf16_f32 v253, v94, v95
	v_add_f32_e32 v209, v209, v80
	v_add_f32_e32 v211, v211, v81
	v_add_f32_e32 v213, v213, v82
	s_waitcnt lgkmcnt(4)
	v_mfma_f32_32x32x16_bf16 v[0:15], v[112:115], v[124:127], v[0:15]
	v_add_f32_e32 v215, v215, v83
	v_add_f32_e32 v209, v209, v84
	v_add_f32_e32 v211, v211, v85
	v_add_f32_e32 v213, v213, v86
	v_add_f32_e32 v215, v215, v87
	s_waitcnt lgkmcnt(3)
	v_mfma_f32_32x32x16_bf16 v[48:63], v[64:67], v[250:253], v[48:63]
	v_add_f32_e32 v209, v209, v88
	v_add_f32_e32 v211, v211, v89
	s_waitcnt lgkmcnt(2)
	v_mfma_f32_32x32x16_bf16 v[32:47], v[72:75], v[250:253], v[32:47]
	v_add_f32_e32 v213, v213, v90
	v_add_f32_e32 v215, v215, v91
	s_waitcnt lgkmcnt(1)
	v_mfma_f32_32x32x16_bf16 v[16:31], v[76:79], v[250:253], v[16:31]
	v_add_f32_e32 v209, v209, v92
	v_add_f32_e32 v211, v211, v93
	s_waitcnt lgkmcnt(0)
	v_mfma_f32_32x32x16_bf16 v[0:15], v[68:71], v[250:253], v[0:15]
	v_add_f32_e32 v213, v213, v94
	v_add_f32_e32 v215, v215, v95
	v_add_f32_e32 v209, v209, v211
	v_add_f32_e32 v213, v213, v215
	v_add_f32_e32 v209, v209, v213
	v_add_f32_e32 v205, v205, v209
	s_waitcnt vmcnt(0)
	s_add_i32 s30, s52, 1
	s_cmp_lg_u32 s52, 2
	s_cselect_b32 s57, s30, 0
	s_add_i32 s55, s55, 1
	s_add_i32 s49, s49, 64
	s_add_i32 s51, s51, 64
	s_mov_b32 s56, s53
	s_mov_b32 s53, s52
	s_mov_b32 s52, s57
	s_mul_i32 s30, s56, 0x6400
	v_add_u32_e32 v209, s30, v246
	s_mul_i32 s30, s56, 0x4800
	v_add_u32_e32 v219, s30, v247
	s_cmp_eq_u32 s20, s55
	s_waitcnt lgkmcnt(0)
	s_barrier
	s_cbranch_scc0 .LBB0_178
	s_barrier
	s_branch .LBB0_153

.Latt_mlaT_norescale:
	v_exp_f32_e32 v64, v64
	v_exp_f32_e32 v65, v65
	v_exp_f32_e32 v66, v66
	v_exp_f32_e32 v67, v67
	v_exp_f32_e32 v68, v68
	v_exp_f32_e32 v69, v69
	v_exp_f32_e32 v70, v70
	v_exp_f32_e32 v71, v71
	v_cvt_pk_bf16_f32 v124, v64, v65
	v_cvt_pk_bf16_f32 v125, v66, v67
	v_cvt_pk_bf16_f32 v126, v68, v69
	v_cvt_pk_bf16_f32 v127, v70, v71
	s_waitcnt vmcnt(0)
	s_barrier
	s_add_i32 s30, s55, 2
	s_cmp_ge_u32 s30, s20
	s_cselect_b64 s[60:61], -1, 0
	s_cbranch_scc1 .Latt_mlaT_dmaend
	s_cmp_lt_u32 s55, 2
	s_cselect_b32 s62, s51, s49
	s_mul_i32 s57, s52, 0x6400
	s_add_i32 s57, s57, s42
	s_mov_b32 m0, s57
	v_mad_u32_u24 v217, s62, v237, v222
	global_load_lds_dwordx4 v217, s[2:3]
	s_add_i32 m0, s57, 0x2000
	v_mad_u32_u24 v217, s62, v239, v224
	global_load_lds_dwordx4 v217, s[2:3]
	s_add_i32 m0, s57, 0x4000
	v_mad_u32_u24 v217, s62, v241, v226
	global_load_lds_dwordx4 v217, s[2:3]
	s_ashr_i32 s63, s62, 31
	s_lshl_b64 s[30:31], s[62:63], 1
	s_mul_i32 s63, s52, 0x4800
	s_add_i32 s63, s63, s42
	s_add_i32 m0, s63, 0x12c00
	s_add_u32 s30, s21, s30
	s_addc_u32 s31, s43, s31
	global_load_lds_dwordx4 v202, s[30:31]
	s_add_i32 m0, s63, 0x14c00
	s_and_b64 vcc, exec, s[18:19]
	global_load_lds_dwordx4 v200, s[30:31]
	s_cbranch_vccz .Latt_mlaT_dmax
.Latt_mlaT_dmaend:
	s_waitcnt lgkmcnt(2)
	s_nop 0
	v_mfma_f32_32x32x16_bf16 v[48:63], v[112:115], v[124:127], v[48:63]
	ds_read_b128 v[112:115], v219 offset:13824
	v_exp_f32_e32 v72, v72
	v_exp_f32_e32 v73, v73
	v_exp_f32_e32 v74, v74
	v_exp_f32_e32 v75, v75
	s_waitcnt lgkmcnt(2)
	v_mfma_f32_32x32x16_bf16 v[32:47], v[116:119], v[124:127], v[32:47]
	ds_read_b128 v[116:119], v219 offset:32
	v_cvt_pk_bf16_f32 v250, v72, v73
	v_exp_f32_e32 v76, v76
	v_exp_f32_e32 v77, v77
	v_cvt_pk_bf16_f32 v251, v74, v75
	s_waitcnt lgkmcnt(2)
	v_mfma_f32_32x32x16_bf16 v[16:31], v[120:123], v[124:127], v[16:31]
	ds_read_b128 v[120:123], v219 offset:4640
	v_exp_f32_e32 v78, v78
	v_exp_f32_e32 v79, v79
	v_cvt_pk_bf16_f32 v252, v76, v77
	v_cvt_pk_bf16_f32 v253, v78, v79
	s_waitcnt lgkmcnt(2)
	v_mfma_f32_32x32x16_bf16 v[0:15], v[112:115], v[124:127], v[0:15]
	ds_read_b128 v[112:115], v219 offset:9248
	v_add_f32_e32 v209, v64, v68
	v_add_f32_e32 v211, v65, v69
	v_add_f32_e32 v213, v66, v70
	v_add_f32_e32 v215, v67, v71
	s_waitcnt lgkmcnt(2)
	v_mfma_f32_32x32x16_bf16 v[48:63], v[116:119], v[250:253], v[48:63]
	ds_read_b128 v[64:67], v219 offset:13856
	ds_read_b128 v[68:71], v219 offset:64
	v_exp_f32_e32 v80, v80
	v_exp_f32_e32 v81, v81
	v_exp_f32_e32 v82, v82
	v_exp_f32_e32 v83, v83
	v_cvt_pk_bf16_f32 v124, v80, v81
	s_waitcnt lgkmcnt(3)
	v_mfma_f32_32x32x16_bf16 v[32:47], v[120:123], v[250:253], v[32:47]
	ds_read_b128 v[116:119], v219 offset:4672
	ds_read_b128 v[120:123], v219 offset:9280
	v_exp_f32_e32 v84, v84
	v_exp_f32_e32 v85, v85
	v_cvt_pk_bf16_f32 v125, v82, v83
	v_exp_f32_e32 v86, v86
	v_exp_f32_e32 v87, v87
	s_waitcnt lgkmcnt(4)
	v_mfma_f32_32x32x16_bf16 v[16:31], v[112:115], v[250:253], v[16:31]
	ds_read_b128 v[112:115], v219 offset:13888
	v_cvt_pk_bf16_f32 v126, v84, v85
	v_cvt_pk_bf16_f32 v127, v86, v87
	v_add_f32_e32 v209, v209, v72
	v_add_f32_e32 v211, v211, v73
	v_add_f32_e32 v213, v213, v74
	s_waitcnt lgkmcnt(4)
	v_mfma_f32_32x32x16_bf16 v[0:15], v[64:67], v[250:253], v[0:15]
	ds_read_b128 v[64:67], v219 offset:96
	v_add_f32_e32 v215, v215, v75
	v_add_f32_e32 v209, v209, v76
	v_add_f32_e32 v211, v211, v77
	v_add_f32_e32 v213, v213, v78
	v_add_f32_e32 v215, v215, v79
	s_waitcnt lgkmcnt(4)
	v_mfma_f32_32x32x16_bf16 v[48:63], v[68:71], v[124:127], v[48:63]
	ds_read_b128 v[72:75], v219 offset:4704
	ds_read_b128 v[76:79], v219 offset:9312
	v_exp_f32_e32 v88, v88
	v_exp_f32_e32 v89, v89
	v_exp_f32_e32 v90, v90
	v_exp_f32_e32 v91, v91
	v_cvt_pk_bf16_f32 v250, v88, v89
	s_waitcnt lgkmcnt(5)
	v_mfma_f32_32x32x16_bf16 v[32:47], v[116:119], v[124:127], v[32:47]
	ds_read_b128 v[68:71], v219 offset:13920
	v_exp_f32_e32 v92, v92
	v_exp_f32_e32 v93, v93
	v_cvt_pk_bf16_f32 v251, v90, v91
	v_exp_f32_e32 v94, v94
	v_exp_f32_e32 v95, v95
	s_waitcnt lgkmcnt(5)
	v_mfma_f32_32x32x16_bf16 v[16:31], v[120:123], v[124:127], v[16:31]
	v_cvt_pk_bf16_f32 v252, v92, v93
	v_cvt_pk_bf16_f32 v253, v94, v95
	v_add_f32_e32 v209, v209, v80
	v_add_f32_e32 v211, v211, v81
	v_add_f32_e32 v213, v213, v82
	s_waitcnt lgkmcnt(4)
	v_mfma_f32_32x32x16_bf16 v[0:15], v[112:115], v[124:127], v[0:15]
	v_add_f32_e32 v215, v215, v83
	v_add_f32_e32 v209, v209, v84
	v_add_f32_e32 v211, v211, v85
	v_add_f32_e32 v213, v213, v86
	v_add_f32_e32 v215, v215, v87
	s_waitcnt lgkmcnt(3)
	v_mfma_f32_32x32x16_bf16 v[48:63], v[64:67], v[250:253], v[48:63]
	v_add_f32_e32 v209, v209, v88
	v_add_f32_e32 v211, v211, v89
	s_waitcnt lgkmcnt(2)
	v_mfma_f32_32x32x16_bf16 v[32:47], v[72:75], v[250:253], v[32:47]
	v_add_f32_e32 v213, v213, v90
	v_add_f32_e32 v215, v215, v91
	s_waitcnt lgkmcnt(1)
	v_mfma_f32_32x32x16_bf16 v[16:31], v[76:79], v[250:253], v[16:31]
	v_add_f32_e32 v209, v209, v92
	v_add_f32_e32 v211, v211, v93
	s_waitcnt lgkmcnt(0)
	v_mfma_f32_32x32x16_bf16 v[0:15], v[68:71], v[250:253], v[0:15]
	v_add_f32_e32 v213, v213, v94
	v_add_f32_e32 v215, v215, v95
	v_add_f32_e32 v209, v209, v211
	v_add_f32_e32 v213, v213, v215
	v_add_f32_e32 v209, v209, v213
	v_add_f32_e32 v205, v205, v209
	s_add_i32 s30, s52, 1
	s_cmp_lg_u32 s52, 2
	s_cselect_b32 s57, s30, 0
	s_add_i32 s55, s55, 1
	s_add_i32 s49, s49, 64
	s_add_i32 s51, s51, 64
	s_mov_b32 s56, s53
	s_mov_b32 s53, s52
	s_mov_b32 s52, s57
	s_mul_i32 s30, s56, 0x6400
	v_add_u32_e32 v209, s30, v246
	s_mul_i32 s30, s56, 0x4800
	v_add_u32_e32 v219, s30, v247
	s_cmp_eq_u32 s20, s55
	s_cbranch_scc0 .Latt_mlaT_top
	s_barrier
	s_branch .LBB0_153
.Latt_mlaL_dmax:
	s_add_i32 m0, s63, 0x16c00
	s_and_b64 vcc, exec, s[12:13]
	global_load_lds_dwordx4 v198, s[30:31]
	s_cbranch_vccnz .Latt_mlaL_dmaend
	s_add_i32 m0, s57, 0x6000
	v_mad_u32_u24 v217, s62, v243, v228
	global_load_lds_dwordx4 v217, s[2:3]
	s_branch .Latt_mlaL_dmaend
.Latt_mlaT_dmax:
	s_add_i32 m0, s63, 0x16c00
	s_and_b64 vcc, exec, s[12:13]
	global_load_lds_dwordx4 v198, s[30:31]
	s_cbranch_vccnz .Latt_mlaT_dmaend
	s_add_i32 m0, s57, 0x6000
	v_mad_u32_u24 v217, s62, v243, v228
	global_load_lds_dwordx4 v217, s[2:3]
	s_branch .Latt_mlaT_dmaend
.Latt_mlaL_rare:
	v_mov_b32_e32 v211, v209
	s_nop 1
	v_permlane32_swap_b32_e32 v209, v211
	v_max_f32_e32 v217, v209, v211
	v_max_f32_e32 v211, s31, v217
	v_max_f32_e32 v213, 0, v211
	v_add_f32_e32 v207, v207, v211
	v_exp_f32_e64 v250, -v213
	v_sub_f32_e32 v96, v96, v211
	v_mov_b32_e32 v97, v96
	v_mov_b32_e32 v98, v96
	v_mov_b32_e32 v99, v96
	v_mov_b32_e32 v100, v96
	v_mov_b32_e32 v101, v96
	v_mov_b32_e32 v102, v96
	v_mov_b32_e32 v103, v96
	v_mov_b32_e32 v104, v96
	v_mov_b32_e32 v105, v96
	v_mov_b32_e32 v106, v96
	v_mov_b32_e32 v107, v96
	v_mov_b32_e32 v108, v96
	v_mov_b32_e32 v109, v96
	v_mov_b32_e32 v110, v96
	v_mov_b32_e32 v111, v96
	v_sub_f32_e32 v64, v64, v211
	v_sub_f32_e32 v65, v65, v211
	v_sub_f32_e32 v66, v66, v211
	v_sub_f32_e32 v67, v67, v211
	v_sub_f32_e32 v68, v68, v211
	v_sub_f32_e32 v69, v69, v211
	v_sub_f32_e32 v70, v70, v211
	v_sub_f32_e32 v71, v71, v211
	v_sub_f32_e32 v72, v72, v211
	v_sub_f32_e32 v73, v73, v211
	v_sub_f32_e32 v74, v74, v211
	v_sub_f32_e32 v75, v75, v211
	v_sub_f32_e32 v76, v76, v211
	v_sub_f32_e32 v77, v77, v211
	v_sub_f32_e32 v78, v78, v211
	v_sub_f32_e32 v79, v79, v211
	v_sub_f32_e32 v80, v80, v211
	v_sub_f32_e32 v81, v81, v211
	v_sub_f32_e32 v82, v82, v211
	v_sub_f32_e32 v83, v83, v211
	v_sub_f32_e32 v84, v84, v211
	v_sub_f32_e32 v85, v85, v211
	v_sub_f32_e32 v86, v86, v211
	v_sub_f32_e32 v87, v87, v211
	v_sub_f32_e32 v88, v88, v211
	v_sub_f32_e32 v89, v89, v211
	v_sub_f32_e32 v90, v90, v211
	v_sub_f32_e32 v91, v91, v211
	v_sub_f32_e32 v92, v92, v211
	v_sub_f32_e32 v93, v93, v211
	v_sub_f32_e32 v94, v94, v211
	v_sub_f32_e32 v95, v95, v211
	v_mul_f32_e32 v205, v205, v250
	v_pk_mul_f32 v[48:49], v[48:49], v[250:251] op_sel_hi:[1,0]
	v_pk_mul_f32 v[50:51], v[50:51], v[250:251] op_sel_hi:[1,0]
	v_pk_mul_f32 v[52:53], v[52:53], v[250:251] op_sel_hi:[1,0]
	v_pk_mul_f32 v[54:55], v[54:55], v[250:251] op_sel_hi:[1,0]
	v_pk_mul_f32 v[56:57], v[56:57], v[250:251] op_sel_hi:[1,0]
	v_pk_mul_f32 v[58:59], v[58:59], v[250:251] op_sel_hi:[1,0]
	v_pk_mul_f32 v[60:61], v[60:61], v[250:251] op_sel_hi:[1,0]
	v_pk_mul_f32 v[62:63], v[62:63], v[250:251] op_sel_hi:[1,0]
	v_pk_mul_f32 v[32:33], v[32:33], v[250:251] op_sel_hi:[1,0]
	v_pk_mul_f32 v[34:35], v[34:35], v[250:251] op_sel_hi:[1,0]
	v_pk_mul_f32 v[36:37], v[36:37], v[250:251] op_sel_hi:[1,0]
	v_pk_mul_f32 v[38:39], v[38:39], v[250:251] op_sel_hi:[1,0]
	v_pk_mul_f32 v[40:41], v[40:41], v[250:251] op_sel_hi:[1,0]
	v_pk_mul_f32 v[42:43], v[42:43], v[250:251] op_sel_hi:[1,0]
	v_pk_mul_f32 v[44:45], v[44:45], v[250:251] op_sel_hi:[1,0]
	v_pk_mul_f32 v[46:47], v[46:47], v[250:251] op_sel_hi:[1,0]
	v_pk_mul_f32 v[16:17], v[16:17], v[250:251] op_sel_hi:[1,0]
	v_pk_mul_f32 v[18:19], v[18:19], v[250:251] op_sel_hi:[1,0]
	v_pk_mul_f32 v[20:21], v[20:21], v[250:251] op_sel_hi:[1,0]
	v_pk_mul_f32 v[22:23], v[22:23], v[250:251] op_sel_hi:[1,0]
	v_pk_mul_f32 v[24:25], v[24:25], v[250:251] op_sel_hi:[1,0]
	v_pk_mul_f32 v[26:27], v[26:27], v[250:251] op_sel_hi:[1,0]
	v_pk_mul_f32 v[28:29], v[28:29], v[250:251] op_sel_hi:[1,0]
	v_pk_mul_f32 v[30:31], v[30:31], v[250:251] op_sel_hi:[1,0]
	v_pk_mul_f32 v[0:1], v[0:1], v[250:251] op_sel_hi:[1,0]
	v_pk_mul_f32 v[2:3], v[2:3], v[250:251] op_sel_hi:[1,0]
	v_pk_mul_f32 v[4:5], v[4:5], v[250:251] op_sel_hi:[1,0]
	v_pk_mul_f32 v[6:7], v[6:7], v[250:251] op_sel_hi:[1,0]
	v_pk_mul_f32 v[8:9], v[8:9], v[250:251] op_sel_hi:[1,0]
	v_pk_mul_f32 v[10:11], v[10:11], v[250:251] op_sel_hi:[1,0]
	v_pk_mul_f32 v[12:13], v[12:13], v[250:251] op_sel_hi:[1,0]
	v_pk_mul_f32 v[14:15], v[14:15], v[250:251] op_sel_hi:[1,0]
	s_branch .Latt_mlaL_norescale
.Latt_mlaT_rare:
	v_mov_b32_e32 v211, v209
	s_nop 1
	v_permlane32_swap_b32_e32 v209, v211
	v_max_f32_e32 v217, v209, v211
	v_max_f32_e32 v211, s31, v217
	v_max_f32_e32 v213, 0, v211
	v_add_f32_e32 v207, v207, v211
	v_exp_f32_e64 v250, -v213
	v_sub_f32_e32 v96, v96, v211
	v_mov_b32_e32 v97, v96
	v_mov_b32_e32 v98, v96
	v_mov_b32_e32 v99, v96
	v_mov_b32_e32 v100, v96
	v_mov_b32_e32 v101, v96
	v_mov_b32_e32 v102, v96
	v_mov_b32_e32 v103, v96
	v_mov_b32_e32 v104, v96
	v_mov_b32_e32 v105, v96
	v_mov_b32_e32 v106, v96
	v_mov_b32_e32 v107, v96
	v_mov_b32_e32 v108, v96
	v_mov_b32_e32 v109, v96
	v_mov_b32_e32 v110, v96
	v_mov_b32_e32 v111, v96
	v_sub_f32_e32 v64, v64, v211
	v_sub_f32_e32 v65, v65, v211
	v_sub_f32_e32 v66, v66, v211
	v_sub_f32_e32 v67, v67, v211
	v_sub_f32_e32 v68, v68, v211
	v_sub_f32_e32 v69, v69, v211
	v_sub_f32_e32 v70, v70, v211
	v_sub_f32_e32 v71, v71, v211
	v_sub_f32_e32 v72, v72, v211
	v_sub_f32_e32 v73, v73, v211
	v_sub_f32_e32 v74, v74, v211
	v_sub_f32_e32 v75, v75, v211
	v_sub_f32_e32 v76, v76, v211
	v_sub_f32_e32 v77, v77, v211
	v_sub_f32_e32 v78, v78, v211
	v_sub_f32_e32 v79, v79, v211
	v_sub_f32_e32 v80, v80, v211
	v_sub_f32_e32 v81, v81, v211
	v_sub_f32_e32 v82, v82, v211
	v_sub_f32_e32 v83, v83, v211
	v_sub_f32_e32 v84, v84, v211
	v_sub_f32_e32 v85, v85, v211
	v_sub_f32_e32 v86, v86, v211
	v_sub_f32_e32 v87, v87, v211
	v_sub_f32_e32 v88, v88, v211
	v_sub_f32_e32 v89, v89, v211
	v_sub_f32_e32 v90, v90, v211
	v_sub_f32_e32 v91, v91, v211
	v_sub_f32_e32 v92, v92, v211
	v_sub_f32_e32 v93, v93, v211
	v_sub_f32_e32 v94, v94, v211
	v_sub_f32_e32 v95, v95, v211
	v_mul_f32_e32 v205, v205, v250
	v_pk_mul_f32 v[48:49], v[48:49], v[250:251] op_sel_hi:[1,0]
	v_pk_mul_f32 v[50:51], v[50:51], v[250:251] op_sel_hi:[1,0]
	v_pk_mul_f32 v[52:53], v[52:53], v[250:251] op_sel_hi:[1,0]
	v_pk_mul_f32 v[54:55], v[54:55], v[250:251] op_sel_hi:[1,0]
	v_pk_mul_f32 v[56:57], v[56:57], v[250:251] op_sel_hi:[1,0]
	v_pk_mul_f32 v[58:59], v[58:59], v[250:251] op_sel_hi:[1,0]
	v_pk_mul_f32 v[60:61], v[60:61], v[250:251] op_sel_hi:[1,0]
	v_pk_mul_f32 v[62:63], v[62:63], v[250:251] op_sel_hi:[1,0]
	v_pk_mul_f32 v[32:33], v[32:33], v[250:251] op_sel_hi:[1,0]
	v_pk_mul_f32 v[34:35], v[34:35], v[250:251] op_sel_hi:[1,0]
	v_pk_mul_f32 v[36:37], v[36:37], v[250:251] op_sel_hi:[1,0]
	v_pk_mul_f32 v[38:39], v[38:39], v[250:251] op_sel_hi:[1,0]
	v_pk_mul_f32 v[40:41], v[40:41], v[250:251] op_sel_hi:[1,0]
	v_pk_mul_f32 v[42:43], v[42:43], v[250:251] op_sel_hi:[1,0]
	v_pk_mul_f32 v[44:45], v[44:45], v[250:251] op_sel_hi:[1,0]
	v_pk_mul_f32 v[46:47], v[46:47], v[250:251] op_sel_hi:[1,0]
	v_pk_mul_f32 v[16:17], v[16:17], v[250:251] op_sel_hi:[1,0]
	v_pk_mul_f32 v[18:19], v[18:19], v[250:251] op_sel_hi:[1,0]
	v_pk_mul_f32 v[20:21], v[20:21], v[250:251] op_sel_hi:[1,0]
	v_pk_mul_f32 v[22:23], v[22:23], v[250:251] op_sel_hi:[1,0]
	v_pk_mul_f32 v[24:25], v[24:25], v[250:251] op_sel_hi:[1,0]
	v_pk_mul_f32 v[26:27], v[26:27], v[250:251] op_sel_hi:[1,0]
	v_pk_mul_f32 v[28:29], v[28:29], v[250:251] op_sel_hi:[1,0]
	v_pk_mul_f32 v[30:31], v[30:31], v[250:251] op_sel_hi:[1,0]
	v_pk_mul_f32 v[0:1], v[0:1], v[250:251] op_sel_hi:[1,0]
	v_pk_mul_f32 v[2:3], v[2:3], v[250:251] op_sel_hi:[1,0]
	v_pk_mul_f32 v[4:5], v[4:5], v[250:251] op_sel_hi:[1,0]
	v_pk_mul_f32 v[6:7], v[6:7], v[250:251] op_sel_hi:[1,0]
	v_pk_mul_f32 v[8:9], v[8:9], v[250:251] op_sel_hi:[1,0]
	v_pk_mul_f32 v[10:11], v[10:11], v[250:251] op_sel_hi:[1,0]
	v_pk_mul_f32 v[12:13], v[12:13], v[250:251] op_sel_hi:[1,0]
	v_pk_mul_f32 v[14:15], v[14:15], v[250:251] op_sel_hi:[1,0]
	s_branch .Latt_mlaT_norescale
